# in-proj epilogue: row scales from LDS and no vmcnt(0) at the epilogue start (next-tile prefetch stays in flight)
# speedup vs baseline: 1.0068x; 1.0043x over previous
.LBB0_269:
	s_lshl_b32 s23, s42, 8
	s_add_i32 s23, s23, s80
	v_or_b32_e32 v174, s23, v145
	v_ashrrev_i32_e32 v175, 31, v174
	s_mov_b32 s100, 0x20000
	v_and_b32_e32 v128, 0xff, v174
	v_lshl_add_u32 v128, v128, 2, s100
	ds_read_b32 v130, v128
	ds_read_b32 v131, v128 offset:64
	ds_read_b32 v132, v128 offset:128
	ds_read_b32 v133, v128 offset:192
	ds_read_b32 v134, v128 offset:512
	ds_read_b32 v135, v128 offset:576
	ds_read_b32 v156, v128 offset:640
	s_nop 0
	ds_read_b32 v128, v128 offset:704
	v_add_u32_e32 v164, 0x80, v174
	v_ashrrev_i32_e32 v165, 31, v164
	s_mov_b64 s[30:31], -1
	s_cmp_lg_u32 s49, 15
	s_waitcnt lgkmcnt(0)
	v_fmamk_f32 v129, v130, 0x3a800000, v192
	v_cmp_gt_f32_e32 vcc, s93, v129
	v_mul_f32_e32 v130, 0x4b800000, v129
	v_fmamk_f32 v128, v128, 0x3a800000, v192
	v_cndmask_b32_e32 v129, v129, v130, vcc
	v_rsq_f32_e32 v129, v129
	s_nop 0
	v_mul_f32_e32 v130, 0x45800000, v129
	v_cndmask_b32_e32 v172, v129, v130, vcc
	v_fmamk_f32 v129, v131, 0x3a800000, v192
	v_cmp_gt_f32_e32 vcc, s93, v129
	v_mul_f32_e32 v130, 0x4b800000, v129
	s_nop 0
	v_cndmask_b32_e32 v129, v129, v130, vcc
	v_rsq_f32_e32 v129, v129
	s_nop 0
	v_mul_f32_e32 v130, 0x45800000, v129
	v_cndmask_b32_e32 v170, v129, v130, vcc
	v_fmamk_f32 v129, v132, 0x3a800000, v192
	v_cmp_gt_f32_e32 vcc, s93, v129
	v_mul_f32_e32 v130, 0x4b800000, v129
	s_nop 0
	v_cndmask_b32_e32 v129, v129, v130, vcc
	v_rsq_f32_e32 v129, v129
	s_nop 0
	v_mul_f32_e32 v130, 0x45800000, v129
	v_cndmask_b32_e32 v168, v129, v130, vcc
	v_fmamk_f32 v129, v133, 0x3a800000, v192
	v_cmp_gt_f32_e32 vcc, s93, v129
	v_mul_f32_e32 v130, 0x4b800000, v129
	s_nop 0
	v_cndmask_b32_e32 v129, v129, v130, vcc
	v_rsq_f32_e32 v129, v129
	s_nop 0
	v_mul_f32_e32 v130, 0x45800000, v129
	v_cndmask_b32_e32 v166, v129, v130, vcc
	v_fmamk_f32 v129, v134, 0x3a800000, v192
	v_cmp_gt_f32_e32 vcc, s93, v129
	v_mul_f32_e32 v130, 0x4b800000, v129
	s_nop 0
	v_cndmask_b32_e32 v129, v129, v130, vcc
	v_rsq_f32_e32 v129, v129
	s_nop 0
	v_mul_f32_e32 v130, 0x45800000, v129
	v_cndmask_b32_e32 v162, v129, v130, vcc
	v_fmamk_f32 v129, v135, 0x3a800000, v192
	v_cmp_gt_f32_e32 vcc, s93, v129
	v_mul_f32_e32 v130, 0x4b800000, v129
	s_nop 0
	v_cndmask_b32_e32 v129, v129, v130, vcc
	v_rsq_f32_e32 v129, v129
	s_nop 0
	v_mul_f32_e32 v130, 0x45800000, v129
	v_cndmask_b32_e32 v160, v129, v130, vcc
	v_fmamk_f32 v129, v156, 0x3a800000, v192
	v_cmp_gt_f32_e32 vcc, s93, v129
	v_mul_f32_e32 v130, 0x4b800000, v129
	s_nop 0
	v_cndmask_b32_e32 v129, v129, v130, vcc
	v_rsq_f32_e32 v129, v129
	s_nop 0
	v_mul_f32_e32 v130, 0x45800000, v129
	v_cndmask_b32_e32 v158, v129, v130, vcc
	v_cmp_gt_f32_e32 vcc, s93, v128
	v_mul_f32_e32 v129, 0x4b800000, v128
	s_nop 0
	v_cndmask_b32_e32 v128, v128, v129, vcc
	v_rsq_f32_e32 v128, v128
	s_nop 0
	v_mul_f32_e32 v129, 0x45800000, v128
	v_cndmask_b32_e32 v156, v128, v129, vcc
	s_cbranch_scc1 .LBB0_272
	s_and_b64 vcc, exec, s[30:31]
	s_cbranch_vccnz .LBB0_477
